# in-proj/up K-loops: counted lgkmcnt waits in front of the first consumer MFMA instead of lgkmcnt(0) at MFMA section head (on top of SGPR-base LDS-DMA addressing)
# speedup vs baseline: 1.0080x; 1.0042x over previous
.LBB0_138:
	s_add_u32 s6, s0, 0xfff80080
	s_addc_u32 s7, s1, -1
	s_add_i32 s76, 0, 0x10000
	v_add_u32_e32 v0, s76, v149
	ds_read_b128 v[130:133], v0
	ds_read_b128 v[134:137], v0 offset:1024
	ds_read_b128 v[138:141], v0 offset:2048
	ds_read_b128 v[142:145], v0 offset:3072
	s_cmp_eq_u32 s49, 28
	s_cselect_b32 s13, s51, s7
	s_cselect_b32 s12, s50, s6
	s_cselect_b32 s7, s22, s39
	s_cselect_b32 s6, s23, s38
	s_add_i32 m0, s31, 0xc000
	ds_read_b128 v[152:155], v174
	ds_read_b128 v[166:169], v174 offset:1024
	ds_read_b128 v[170:173], v174 offset:2048
	ds_read_b128 v[176:179], v174 offset:3072
	ds_read_b128 v[180:183], v174 offset:4096
	ds_read_b128 v[184:187], v174 offset:5120
	ds_read_b128 v[188:191], v174 offset:6144
	ds_read_b128 v[192:195], v174 offset:7168
	global_load_lds_dwordx4 v162, s[0:1]
	s_add_i32 m0, s31, 0xe000
	s_nop 0
	global_load_lds_dwordx4 v164, s[0:1]
	s_waitcnt lgkmcnt(8)
	s_barrier
	s_setprio 1
	s_waitcnt lgkmcnt(7)
	v_mfma_f32_16x16x32_bf16 v[126:129], v[130:133], v[152:155], v[126:129]
	v_mfma_f32_16x16x32_bf16 v[122:125], v[138:141], v[152:155], v[122:125]
	s_waitcnt lgkmcnt(5)
	v_mfma_f32_16x16x32_bf16 v[114:117], v[130:133], v[170:173], v[114:117]
	v_mfma_f32_16x16x32_bf16 v[106:109], v[138:141], v[170:173], v[106:109]
	s_waitcnt lgkmcnt(3)
	v_mfma_f32_16x16x32_bf16 v[98:101], v[130:133], v[180:183], v[98:101]
	v_mfma_f32_16x16x32_bf16 v[90:93], v[138:141], v[180:183], v[90:93]
	s_waitcnt lgkmcnt(1)
	v_mfma_f32_16x16x32_bf16 v[82:85], v[130:133], v[188:191], v[82:85]
	v_mfma_f32_16x16x32_bf16 v[74:77], v[138:141], v[188:191], v[74:77]
	v_mfma_f32_16x16x32_bf16 v[126:129], v[134:137], v[166:169], v[126:129]
	v_mfma_f32_16x16x32_bf16 v[122:125], v[142:145], v[166:169], v[122:125]
	v_mfma_f32_16x16x32_bf16 v[114:117], v[134:137], v[176:179], v[114:117]
	v_mfma_f32_16x16x32_bf16 v[106:109], v[142:145], v[176:179], v[106:109]
	v_mfma_f32_16x16x32_bf16 v[98:101], v[134:137], v[184:187], v[98:101]
	v_mfma_f32_16x16x32_bf16 v[90:93], v[142:145], v[184:187], v[90:93]
	s_waitcnt lgkmcnt(0)
	v_mfma_f32_16x16x32_bf16 v[82:85], v[134:137], v[192:195], v[82:85]
	v_mfma_f32_16x16x32_bf16 v[74:77], v[142:145], v[192:195], v[74:77]
	s_setprio 0
	s_barrier
	s_add_i32 s78, 0, 0x14000
	s_add_i32 s76, s76, s30
	v_add_u32_e32 v0, s78, v149
	s_mov_b32 m0, s76
	ds_read_b128 v[196:199], v0
	ds_read_b128 v[200:203], v0 offset:1024
	ds_read_b128 v[204:207], v0 offset:2048
	ds_read_b128 v[216:219], v0 offset:3072
	global_load_lds_dwordx4 v158, s[6:7]
	s_add_i32 m0, s76, 0x2000
	s_nop 0
	global_load_lds_dwordx4 v146, s[6:7]
	s_barrier
	s_setprio 1
	s_waitcnt lgkmcnt(3)
	v_mfma_f32_16x16x32_bf16 v[118:121], v[196:199], v[152:155], v[118:121]
	s_waitcnt lgkmcnt(1)
	v_mfma_f32_16x16x32_bf16 v[110:113], v[204:207], v[152:155], v[110:113]
	v_mfma_f32_16x16x32_bf16 v[102:105], v[196:199], v[170:173], v[102:105]
	v_mfma_f32_16x16x32_bf16 v[94:97], v[204:207], v[170:173], v[94:97]
	v_mfma_f32_16x16x32_bf16 v[86:89], v[196:199], v[180:183], v[86:89]
	v_mfma_f32_16x16x32_bf16 v[78:81], v[204:207], v[180:183], v[78:81]
	v_mfma_f32_16x16x32_bf16 v[70:73], v[196:199], v[188:191], v[70:73]
	v_mfma_f32_16x16x32_bf16 v[66:69], v[204:207], v[188:191], v[66:69]
	v_mfma_f32_16x16x32_bf16 v[118:121], v[200:203], v[166:169], v[118:121]
	s_waitcnt lgkmcnt(0)
	v_mfma_f32_16x16x32_bf16 v[110:113], v[216:219], v[166:169], v[110:113]
	v_mfma_f32_16x16x32_bf16 v[102:105], v[200:203], v[176:179], v[102:105]
	v_mfma_f32_16x16x32_bf16 v[94:97], v[216:219], v[176:179], v[94:97]
	v_mfma_f32_16x16x32_bf16 v[86:89], v[200:203], v[184:187], v[86:89]
	v_mfma_f32_16x16x32_bf16 v[78:81], v[216:219], v[184:187], v[78:81]
	v_mfma_f32_16x16x32_bf16 v[70:73], v[200:203], v[192:195], v[70:73]
	v_mfma_f32_16x16x32_bf16 v[66:69], v[216:219], v[192:195], v[66:69]
	s_setprio 0
	s_mov_b32 m0, s31
	s_add_u32 s98, s12, 0x80
	s_addc_u32 s99, s13, 0
	s_barrier
	ds_read_b128 v[152:155], v174 offset:16384
	ds_read_b128 v[166:169], v174 offset:17408
	ds_read_b128 v[170:173], v174 offset:18432
	ds_read_b128 v[176:179], v174 offset:19456
	ds_read_b128 v[180:183], v174 offset:20480
	ds_read_b128 v[184:187], v174 offset:21504
	ds_read_b128 v[188:191], v174 offset:22528
	ds_read_b128 v[192:195], v174 offset:23552
	global_load_lds_dwordx4 v160, s[12:13]
	s_mov_b32 m0, s40
	s_nop 0
	global_load_lds_dwordx4 v156, s[12:13]
	s_barrier
	s_setprio 1
	s_waitcnt lgkmcnt(7)
	v_mfma_f32_16x16x32_bf16 v[62:65], v[130:133], v[152:155], v[62:65]
	v_mfma_f32_16x16x32_bf16 v[58:61], v[138:141], v[152:155], v[58:61]
	s_waitcnt lgkmcnt(5)
	v_mfma_f32_16x16x32_bf16 v[50:53], v[130:133], v[170:173], v[50:53]
	v_mfma_f32_16x16x32_bf16 v[42:45], v[138:141], v[170:173], v[42:45]
	s_waitcnt lgkmcnt(3)
	v_mfma_f32_16x16x32_bf16 v[34:37], v[130:133], v[180:183], v[34:37]
	v_mfma_f32_16x16x32_bf16 v[26:29], v[138:141], v[180:183], v[26:29]
	s_waitcnt lgkmcnt(1)
	v_mfma_f32_16x16x32_bf16 v[18:21], v[130:133], v[188:191], v[18:21]
	v_mfma_f32_16x16x32_bf16 v[10:13], v[138:141], v[188:191], v[10:13]
	v_mfma_f32_16x16x32_bf16 v[62:65], v[134:137], v[166:169], v[62:65]
	v_mfma_f32_16x16x32_bf16 v[58:61], v[142:145], v[166:169], v[58:61]
	v_mfma_f32_16x16x32_bf16 v[50:53], v[134:137], v[176:179], v[50:53]
	v_mfma_f32_16x16x32_bf16 v[42:45], v[142:145], v[176:179], v[42:45]
	v_mfma_f32_16x16x32_bf16 v[34:37], v[134:137], v[184:187], v[34:37]
	v_mfma_f32_16x16x32_bf16 v[26:29], v[142:145], v[184:187], v[26:29]
	s_waitcnt lgkmcnt(0)
	v_mfma_f32_16x16x32_bf16 v[18:21], v[134:137], v[192:195], v[18:21]
	v_mfma_f32_16x16x32_bf16 v[10:13], v[142:145], v[192:195], v[10:13]
	s_setprio 0
	s_barrier
	s_add_u32 s76, s6, 0x80000
	s_addc_u32 s77, s7, 0
	s_add_i32 s78, s78, s30
	s_mov_b32 m0, s78
	s_nop 0
	global_load_lds_dwordx4 v158, s[76:77]
	s_add_i32 m0, s78, 0x2000
	s_nop 0
	global_load_lds_dwordx4 v146, s[76:77]
	s_waitcnt vmcnt(6)
	s_barrier
	s_setprio 1
	v_mfma_f32_16x16x32_bf16 v[54:57], v[196:199], v[152:155], v[54:57]
	v_mfma_f32_16x16x32_bf16 v[46:49], v[204:207], v[152:155], v[46:49]
	v_mfma_f32_16x16x32_bf16 v[38:41], v[196:199], v[170:173], v[38:41]
	v_mfma_f32_16x16x32_bf16 v[30:33], v[204:207], v[170:173], v[30:33]
	v_mfma_f32_16x16x32_bf16 v[22:25], v[196:199], v[180:183], v[22:25]
	v_mfma_f32_16x16x32_bf16 v[14:17], v[204:207], v[180:183], v[14:17]
	v_mfma_f32_16x16x32_bf16 v[6:9], v[196:199], v[188:191], v[6:9]
	v_mfma_f32_16x16x32_bf16 v[2:5], v[204:207], v[188:191], v[2:5]
	v_mfma_f32_16x16x32_bf16 v[54:57], v[200:203], v[166:169], v[54:57]
	v_mfma_f32_16x16x32_bf16 v[46:49], v[216:219], v[166:169], v[46:49]
	v_mfma_f32_16x16x32_bf16 v[38:41], v[200:203], v[176:179], v[38:41]
	v_mfma_f32_16x16x32_bf16 v[30:33], v[216:219], v[176:179], v[30:33]
	v_mfma_f32_16x16x32_bf16 v[22:25], v[200:203], v[184:187], v[22:25]
	v_mfma_f32_16x16x32_bf16 v[14:17], v[216:219], v[184:187], v[14:17]
	v_mfma_f32_16x16x32_bf16 v[6:9], v[200:203], v[192:195], v[6:9]
	v_mfma_f32_16x16x32_bf16 v[2:5], v[216:219], v[192:195], v[2:5]
	s_setprio 0
	s_add_i32 s76, 0, 0x18000
	v_add_u32_e32 v0, s76, v149
	s_barrier
	ds_read_b128 v[130:133], v0
	ds_read_b128 v[134:137], v0 offset:1024
	ds_read_b128 v[138:141], v0 offset:2048
	ds_read_b128 v[142:145], v0 offset:3072
	s_add_u32 s12, s12, 0x80000
	s_addc_u32 s13, s13, 0
	s_mov_b32 m0, s41
	ds_read_b128 v[152:155], v174 offset:32768
	ds_read_b128 v[166:169], v174 offset:33792
	ds_read_b128 v[170:173], v174 offset:34816
	ds_read_b128 v[176:179], v174 offset:35840
	ds_read_b128 v[180:183], v174 offset:36864
	ds_read_b128 v[184:187], v174 offset:37888
	ds_read_b128 v[188:191], v174 offset:38912
	ds_read_b128 v[192:195], v174 offset:39936
	global_load_lds_dwordx4 v160, s[12:13]
	s_mov_b32 m0, s60
	s_nop 0
	global_load_lds_dwordx4 v156, s[12:13]
	s_waitcnt lgkmcnt(8)
	s_barrier
	s_setprio 1
	s_waitcnt lgkmcnt(7)
	v_mfma_f32_16x16x32_bf16 v[126:129], v[130:133], v[152:155], v[126:129]
	v_mfma_f32_16x16x32_bf16 v[122:125], v[138:141], v[152:155], v[122:125]
	s_waitcnt lgkmcnt(5)
	v_mfma_f32_16x16x32_bf16 v[114:117], v[130:133], v[170:173], v[114:117]
	v_mfma_f32_16x16x32_bf16 v[106:109], v[138:141], v[170:173], v[106:109]
	s_waitcnt lgkmcnt(3)
	v_mfma_f32_16x16x32_bf16 v[98:101], v[130:133], v[180:183], v[98:101]
	v_mfma_f32_16x16x32_bf16 v[90:93], v[138:141], v[180:183], v[90:93]
	s_waitcnt lgkmcnt(1)
	v_mfma_f32_16x16x32_bf16 v[82:85], v[130:133], v[188:191], v[82:85]
	v_mfma_f32_16x16x32_bf16 v[74:77], v[138:141], v[188:191], v[74:77]
	v_mfma_f32_16x16x32_bf16 v[126:129], v[134:137], v[166:169], v[126:129]
	v_mfma_f32_16x16x32_bf16 v[122:125], v[142:145], v[166:169], v[122:125]
	v_mfma_f32_16x16x32_bf16 v[114:117], v[134:137], v[176:179], v[114:117]
	v_mfma_f32_16x16x32_bf16 v[106:109], v[142:145], v[176:179], v[106:109]
	v_mfma_f32_16x16x32_bf16 v[98:101], v[134:137], v[184:187], v[98:101]
	v_mfma_f32_16x16x32_bf16 v[90:93], v[142:145], v[184:187], v[90:93]
	s_waitcnt lgkmcnt(0)
	v_mfma_f32_16x16x32_bf16 v[82:85], v[134:137], v[192:195], v[82:85]
	v_mfma_f32_16x16x32_bf16 v[74:77], v[142:145], v[192:195], v[74:77]
	s_setprio 0
	s_barrier
	s_add_i32 s12, 0, 0x1c000
	s_add_i32 s13, s76, s30
	v_add_u32_e32 v0, s12, v149
	s_add_u32 s100, s6, 0x80
	s_addc_u32 s101, s7, 0
	s_mov_b32 m0, s13
	ds_read_b128 v[196:199], v0
	ds_read_b128 v[200:203], v0 offset:1024
	ds_read_b128 v[204:207], v0 offset:2048
	ds_read_b128 v[216:219], v0 offset:3072
	global_load_lds_dwordx4 v158, s[100:101]
	s_add_i32 m0, s13, 0x2000
	s_nop 0
	global_load_lds_dwordx4 v146, s[100:101]
	s_barrier
	s_setprio 1
	s_waitcnt lgkmcnt(3)
	v_mfma_f32_16x16x32_bf16 v[118:121], v[196:199], v[152:155], v[118:121]
	s_waitcnt lgkmcnt(1)
	v_mfma_f32_16x16x32_bf16 v[110:113], v[204:207], v[152:155], v[110:113]
	v_mfma_f32_16x16x32_bf16 v[102:105], v[196:199], v[170:173], v[102:105]
	v_mfma_f32_16x16x32_bf16 v[94:97], v[204:207], v[170:173], v[94:97]
	v_mfma_f32_16x16x32_bf16 v[86:89], v[196:199], v[180:183], v[86:89]
	v_mfma_f32_16x16x32_bf16 v[78:81], v[204:207], v[180:183], v[78:81]
	v_mfma_f32_16x16x32_bf16 v[70:73], v[196:199], v[188:191], v[70:73]
	v_mfma_f32_16x16x32_bf16 v[66:69], v[204:207], v[188:191], v[66:69]
	v_mfma_f32_16x16x32_bf16 v[118:121], v[200:203], v[166:169], v[118:121]
	s_waitcnt lgkmcnt(0)
	v_mfma_f32_16x16x32_bf16 v[110:113], v[216:219], v[166:169], v[110:113]
	v_mfma_f32_16x16x32_bf16 v[102:105], v[200:203], v[176:179], v[102:105]
	v_mfma_f32_16x16x32_bf16 v[94:97], v[216:219], v[176:179], v[94:97]
	v_mfma_f32_16x16x32_bf16 v[86:89], v[200:203], v[184:187], v[86:89]
	v_mfma_f32_16x16x32_bf16 v[78:81], v[216:219], v[184:187], v[78:81]
	v_mfma_f32_16x16x32_bf16 v[70:73], v[200:203], v[192:195], v[70:73]
	v_mfma_f32_16x16x32_bf16 v[66:69], v[216:219], v[192:195], v[66:69]
	s_setprio 0
	s_mov_b32 m0, s64
	s_barrier
	ds_read_b128 v[152:155], v174 offset:49152
	ds_read_b128 v[166:169], v174 offset:50176
	ds_read_b128 v[170:173], v174 offset:51200
	ds_read_b128 v[176:179], v174 offset:52224
	ds_read_b128 v[180:183], v174 offset:53248
	ds_read_b128 v[184:187], v174 offset:54272
	ds_read_b128 v[188:191], v174 offset:55296
	ds_read_b128 v[192:195], v174 offset:56320
	global_load_lds_dwordx4 v160, s[98:99]
	s_mov_b32 m0, s65
	s_nop 0
	global_load_lds_dwordx4 v156, s[98:99]
	s_barrier
	s_setprio 1
	s_waitcnt lgkmcnt(7)
	v_mfma_f32_16x16x32_bf16 v[62:65], v[130:133], v[152:155], v[62:65]
	v_mfma_f32_16x16x32_bf16 v[58:61], v[138:141], v[152:155], v[58:61]
	s_waitcnt lgkmcnt(5)
	v_mfma_f32_16x16x32_bf16 v[50:53], v[130:133], v[170:173], v[50:53]
	v_mfma_f32_16x16x32_bf16 v[42:45], v[138:141], v[170:173], v[42:45]
	s_waitcnt lgkmcnt(3)
	v_mfma_f32_16x16x32_bf16 v[34:37], v[130:133], v[180:183], v[34:37]
	v_mfma_f32_16x16x32_bf16 v[26:29], v[138:141], v[180:183], v[26:29]
	s_waitcnt lgkmcnt(1)
	v_mfma_f32_16x16x32_bf16 v[18:21], v[130:133], v[188:191], v[18:21]
	v_mfma_f32_16x16x32_bf16 v[10:13], v[138:141], v[188:191], v[10:13]
	v_mfma_f32_16x16x32_bf16 v[62:65], v[134:137], v[166:169], v[62:65]
	v_mfma_f32_16x16x32_bf16 v[58:61], v[142:145], v[166:169], v[58:61]
	v_mfma_f32_16x16x32_bf16 v[50:53], v[134:137], v[176:179], v[50:53]
	v_mfma_f32_16x16x32_bf16 v[42:45], v[142:145], v[176:179], v[42:45]
	v_mfma_f32_16x16x32_bf16 v[34:37], v[134:137], v[184:187], v[34:37]
	v_mfma_f32_16x16x32_bf16 v[26:29], v[142:145], v[184:187], v[26:29]
	s_waitcnt lgkmcnt(0)
	v_mfma_f32_16x16x32_bf16 v[18:21], v[134:137], v[192:195], v[18:21]
	v_mfma_f32_16x16x32_bf16 v[10:13], v[142:145], v[192:195], v[10:13]
	s_setprio 0
	s_barrier
	s_add_u32 s6, s6, 0x80080
	s_addc_u32 s7, s7, 0
	s_add_i32 s12, s12, s30
	s_mov_b32 m0, s12
	s_nop 0
	global_load_lds_dwordx4 v158, s[6:7]
	s_add_i32 m0, s12, 0x2000
	s_nop 0
	global_load_lds_dwordx4 v146, s[6:7]
	s_waitcnt vmcnt(6)
	s_barrier
	s_setprio 1
	v_mfma_f32_16x16x32_bf16 v[54:57], v[196:199], v[152:155], v[54:57]
	v_mfma_f32_16x16x32_bf16 v[46:49], v[204:207], v[152:155], v[46:49]
	v_mfma_f32_16x16x32_bf16 v[38:41], v[196:199], v[170:173], v[38:41]
	v_mfma_f32_16x16x32_bf16 v[30:33], v[204:207], v[170:173], v[30:33]
	v_mfma_f32_16x16x32_bf16 v[22:25], v[196:199], v[180:183], v[22:25]
	v_mfma_f32_16x16x32_bf16 v[14:17], v[204:207], v[180:183], v[14:17]
	v_mfma_f32_16x16x32_bf16 v[6:9], v[196:199], v[188:191], v[6:9]
	v_mfma_f32_16x16x32_bf16 v[2:5], v[204:207], v[188:191], v[2:5]
	v_mfma_f32_16x16x32_bf16 v[54:57], v[200:203], v[166:169], v[54:57]
	v_mfma_f32_16x16x32_bf16 v[46:49], v[216:219], v[166:169], v[46:49]
	v_mfma_f32_16x16x32_bf16 v[38:41], v[200:203], v[176:179], v[38:41]
	v_mfma_f32_16x16x32_bf16 v[30:33], v[216:219], v[176:179], v[30:33]
	v_mfma_f32_16x16x32_bf16 v[22:25], v[200:203], v[184:187], v[22:25]
	v_mfma_f32_16x16x32_bf16 v[14:17], v[216:219], v[184:187], v[14:17]
	v_mfma_f32_16x16x32_bf16 v[6:9], v[200:203], v[192:195], v[6:9]
	v_mfma_f32_16x16x32_bf16 v[2:5], v[216:219], v[192:195], v[2:5]
	s_setprio 0
	s_add_i32 s49, s49, 2
	s_add_u32 s0, s0, 0x100
	s_addc_u32 s1, s1, 0
	s_add_u32 s38, s38, 0x100
	s_addc_u32 s39, s39, 0
	s_cmp_gt_u32 s49, 29
	s_barrier
	s_cbranch_scc0 .LBB0_138
	v_mov_b32_e32 v0, v148
	s_cmp_gt_i32 s69, 15
	v_and_b32_e32 v176, 15, v0
	v_bfe_u32 v175, v0, 4, 2
	s_mov_b64 s[0:1], -1
	s_cbranch_scc0 .LBB0_157
	s_cmp_gt_u32 s69, 23
	s_cbranch_scc0 .LBB0_154
	s_cmp_gt_u32 s69, 31
	s_cbranch_scc0 .LBB0_151
	s_cmp_gt_u32 s69, 39
	s_cbranch_scc0 .LBB0_148
	v_mul_f32_e32 v0, 0xbfb8aa3b, v126
	v_exp_f32_e32 v131, v0
	s_lshr_b32 s0, s75, 3
	s_mulk_i32 s0, 0x880
	s_lshl_b32 s1, s75, 8
	v_add_f32_e32 v131, 1.0, v131
	v_rcp_f32_e32 v132, v131
	v_mul_f32_e32 v131, 0xbfb8aa3b, v122
	v_mul_f32_e32 v133, 0xbfb8aa3b, v127
	v_mul_f32_e32 v134, 0xbfb8aa3b, v123
	v_mul_f32_e32 v135, 0xbfb8aa3b, v128
	v_mul_f32_e32 v136, 0xbfb8aa3b, v124
	v_mul_f32_e32 v137, 0xbfb8aa3b, v129
	v_mul_f32_e32 v138, 0xbfb8aa3b, v125
	v_mul_f32_e32 v139, 0xbfb8aa3b, v118
	v_mul_f32_e32 v140, 0xbfb8aa3b, v110
	v_mul_f32_e32 v141, 0xbfb8aa3b, v119
	v_mul_f32_e32 v142, 0xbfb8aa3b, v111
	v_mul_f32_e32 v143, 0xbfb8aa3b, v120
	v_mul_f32_e32 v152, 0xbfb8aa3b, v112
	v_mul_f32_e32 v153, 0xbfb8aa3b, v121
	v_mul_f32_e32 v154, 0xbfb8aa3b, v113
	v_mul_f32_e32 v155, 0xbfb8aa3b, v114
	v_mul_f32_e32 v177, 0xbfb8aa3b, v106
	v_mul_f32_e32 v178, 0xbfb8aa3b, v115
	v_mul_f32_e32 v179, 0xbfb8aa3b, v107
	v_mul_f32_e32 v180, 0xbfb8aa3b, v116
	v_mul_f32_e32 v181, 0xbfb8aa3b, v108
	v_mul_f32_e32 v182, 0xbfb8aa3b, v117
	v_mul_f32_e32 v183, 0xbfb8aa3b, v109
	v_mul_f32_e32 v184, 0xbfb8aa3b, v102
	v_mul_f32_e32 v185, 0xbfb8aa3b, v94
	v_mul_f32_e32 v186, 0xbfb8aa3b, v103
	v_mul_f32_e32 v187, 0xbfb8aa3b, v95
	v_mul_f32_e32 v188, 0xbfb8aa3b, v104
	v_mul_f32_e32 v189, 0xbfb8aa3b, v96
	v_mul_f32_e32 v190, 0xbfb8aa3b, v105
	v_mul_f32_e32 v191, 0xbfb8aa3b, v97
	v_mul_f32_e32 v192, 0xbfb8aa3b, v98
	v_mul_f32_e32 v193, 0xbfb8aa3b, v90
	v_mul_f32_e32 v194, 0xbfb8aa3b, v99
	v_mul_f32_e32 v195, 0xbfb8aa3b, v91
	v_mul_f32_e32 v196, 0xbfb8aa3b, v100
	v_mul_f32_e32 v197, 0xbfb8aa3b, v92
	v_mul_f32_e32 v198, 0xbfb8aa3b, v101
	v_mul_f32_e32 v199, 0xbfb8aa3b, v93
	v_mul_f32_e32 v200, 0xbfb8aa3b, v86
	v_mul_f32_e32 v201, 0xbfb8aa3b, v78
	v_mul_f32_e32 v202, 0xbfb8aa3b, v87
	v_mul_f32_e32 v203, 0xbfb8aa3b, v79
	v_mul_f32_e32 v204, 0xbfb8aa3b, v88
	v_mul_f32_e32 v205, 0xbfb8aa3b, v80
	v_mul_f32_e32 v206, 0xbfb8aa3b, v89
	v_mul_f32_e32 v207, 0xbfb8aa3b, v81
	v_mul_f32_e32 v208, 0xbfb8aa3b, v82
	v_mul_f32_e32 v209, 0xbfb8aa3b, v74
	v_mul_f32_e32 v215, 0xbfb8aa3b, v83
	v_mul_f32_e32 v216, 0xbfb8aa3b, v75
	v_mul_f32_e32 v217, 0xbfb8aa3b, v84
	v_mul_f32_e32 v218, 0xbfb8aa3b, v76
	v_mul_f32_e32 v219, 0xbfb8aa3b, v85
	v_mul_f32_e32 v220, 0xbfb8aa3b, v77
	v_mul_f32_e32 v221, 0xbfb8aa3b, v70
	v_mul_f32_e32 v222, 0xbfb8aa3b, v66
	v_mul_f32_e32 v223, 0xbfb8aa3b, v71
	v_mul_f32_e32 v224, 0xbfb8aa3b, v67
	v_mul_f32_e32 v225, 0xbfb8aa3b, v72
	v_mul_f32_e32 v226, 0xbfb8aa3b, v68
	v_mul_f32_e32 v227, 0xbfb8aa3b, v73
	v_mul_f32_e32 v228, 0xbfb8aa3b, v69
	v_mul_f32_e32 v229, 0xbfb8aa3b, v62
	v_mul_f32_e32 v230, 0xbfb8aa3b, v58
	v_mul_f32_e32 v231, 0xbfb8aa3b, v63
	v_mul_f32_e32 v232, 0xbfb8aa3b, v59
	v_mul_f32_e32 v233, 0xbfb8aa3b, v64
	v_mul_f32_e32 v234, 0xbfb8aa3b, v60
	v_mul_f32_e32 v235, 0xbfb8aa3b, v65
	v_mul_f32_e32 v236, 0xbfb8aa3b, v61
	v_mul_f32_e32 v237, 0xbfb8aa3b, v54
	v_mul_f32_e32 v238, 0xbfb8aa3b, v46
	v_mul_f32_e32 v239, 0xbfb8aa3b, v55
	s_and_b32 s1, s1, 0x700
	s_add_i32 s0, s0, s66
	v_exp_f32_e32 v173, v131
	v_exp_f32_e32 v133, v133
	v_exp_f32_e32 v172, v134
	v_exp_f32_e32 v171, v135
	v_exp_f32_e32 v170, v136
	v_exp_f32_e32 v169, v137
	v_exp_f32_e32 v131, v138
	v_exp_f32_e32 v168, v139
	v_exp_f32_e32 v167, v140
	v_exp_f32_e32 v166, v141
	v_exp_f32_e32 v145, v142
	v_exp_f32_e32 v144, v143
	v_exp_f32_e32 v143, v152
	v_exp_f32_e32 v142, v153
	v_exp_f32_e32 v141, v154
	v_exp_f32_e32 v140, v155
	v_exp_f32_e32 v139, v177
	v_exp_f32_e32 v138, v178
	v_exp_f32_e32 v213, v179
	v_exp_f32_e32 v155, v180
	v_exp_f32_e32 v154, v181
	v_exp_f32_e32 v153, v182
	v_exp_f32_e32 v152, v183
	v_exp_f32_e32 v212, v184
	v_exp_f32_e32 v211, v185
	v_exp_f32_e32 v252, v186
	v_exp_f32_e32 v251, v187
	v_exp_f32_e32 v250, v188
	v_exp_f32_e32 v249, v189
	v_exp_f32_e32 v248, v190
	v_exp_f32_e32 v247, v191
	v_exp_f32_e32 v246, v192
	v_exp_f32_e32 v245, v193
	v_exp_f32_e32 v244, v194
	v_exp_f32_e32 v243, v195
	v_exp_f32_e32 v242, v196
	v_exp_f32_e32 v241, v197
	v_exp_f32_e32 v184, v198
	v_exp_f32_e32 v177, v199
	v_exp_f32_e32 v198, v200
	v_exp_f32_e32 v199, v201
	v_exp_f32_e32 v197, v202
	v_exp_f32_e32 v196, v203
	v_exp_f32_e32 v195, v204
	v_exp_f32_e32 v194, v205
	v_exp_f32_e32 v193, v206
	v_exp_f32_e32 v192, v207
	v_exp_f32_e32 v191, v208
	v_exp_f32_e32 v190, v209
	v_exp_f32_e32 v189, v215
	v_exp_f32_e32 v188, v216
	v_exp_f32_e32 v187, v217
	v_exp_f32_e32 v186, v218
	v_exp_f32_e32 v185, v219
	v_exp_f32_e32 v201, v220
	v_exp_f32_e32 v200, v221
	v_exp_f32_e32 v221, v222
	v_exp_f32_e32 v220, v223
	v_exp_f32_e32 v219, v224
	v_exp_f32_e32 v218, v225
	v_exp_f32_e32 v217, v226
	v_exp_f32_e32 v216, v227
	v_exp_f32_e32 v215, v228
	v_exp_f32_e32 v209, v229
	v_exp_f32_e32 v208, v230
	v_exp_f32_e32 v207, v231
	v_exp_f32_e32 v206, v232
	v_exp_f32_e32 v205, v233
	v_exp_f32_e32 v204, v234
	v_exp_f32_e32 v203, v235
	v_exp_f32_e32 v202, v236
	v_exp_f32_e32 v223, v237
	v_exp_f32_e32 v222, v238
	v_exp_f32_e32 v238, v239
	s_add_i32 s0, s0, s1
	s_lshl_b32 s1, s69, 8
	v_lshl_or_b32 v130, v175, 3, s1
	s_cmp_gt_u32 s69, 47
	v_or_b32_e32 v240, s0, v176
	v_or_b32_e32 v130, s61, v130
	s_mov_b64 s[0:1], -1
	v_mul_f32_e32 v237, 0xbfb8aa3b, v47
	v_mul_f32_e32 v236, 0xbfb8aa3b, v56
	v_mul_f32_e32 v235, 0xbfb8aa3b, v48
	v_mul_f32_e32 v234, 0xbfb8aa3b, v57
	v_mul_f32_e32 v233, 0xbfb8aa3b, v49
	v_mul_f32_e32 v232, 0xbfb8aa3b, v50
	v_mul_f32_e32 v231, 0xbfb8aa3b, v42
	v_mul_f32_e32 v230, 0xbfb8aa3b, v51
	v_mul_f32_e32 v229, 0xbfb8aa3b, v43
	v_mul_f32_e32 v228, 0xbfb8aa3b, v18
	s_cbranch_scc0 .LBB0_145
	v_add_f32_e32 v178, 1.0, v171
	v_rcp_f32_e32 v179, v178
	v_add_f32_e32 v178, 1.0, v170
	v_add_f32_e32 v134, 1.0, v173
	v_add_f32_e32 v135, 1.0, v133
	v_add_f32_e32 v137, 1.0, v172
	v_rcp_f32_e32 v181, v178
	v_add_f32_e32 v178, 1.0, v169
	v_rcp_f32_e32 v134, v134
	v_rcp_f32_e32 v135, v135
	v_rcp_f32_e32 v137, v137
	v_rcp_f32_e32 v180, v178
	v_add_f32_e32 v178, 1.0, v131
	v_rcp_f32_e32 v182, v178
	v_mov_b32_e32 v0, v240
	v_mov_b32_e32 v136, v130
	v_cvt_pk_bf16_f32 v178, v132, v135
	v_cvt_pk_bf16_f32 v179, v179, v180
	v_cvt_pk_bf16_f32 v180, v134, v137
	v_mov_b64_e32 v[134:135], s[8:9]
	v_ashrrev_i32_e32 v137, 31, v136
	v_cvt_pk_bf16_f32 v181, v181, v182
	v_mad_i64_i32 v[182:183], s[0:1], v0, s47, v[134:135]
	v_lshlrev_b64 v[136:137], 1, v[136:137]
	v_lshl_add_u64 v[182:183], v[182:183], 0, v[136:137]
	global_store_dwordx4 v[182:183], v[178:181], off
	s_nop 1
	v_add_f32_e32 v179, 1.0, v167
	v_add_f32_e32 v178, 1.0, v168
	v_rcp_f32_e32 v180, v179
	v_add_f32_e32 v179, 1.0, v166
	v_add_f32_e32 v181, 1.0, v145
	v_add_f32_e32 v239, 1.0, v144
	v_add_f32_e32 v224, 1.0, v143
	v_add_f32_e32 v225, 1.0, v142
	v_add_f32_e32 v226, 1.0, v141
	v_rcp_f32_e32 v178, v178
	v_rcp_f32_e32 v179, v179
	v_rcp_f32_e32 v181, v181
	v_rcp_f32_e32 v239, v239
	v_rcp_f32_e32 v224, v224
	v_rcp_f32_e32 v225, v225
	v_rcp_f32_e32 v226, v226
	v_cvt_pk_bf16_f32 v178, v178, v179
	v_cvt_pk_bf16_f32 v180, v180, v181
	v_cvt_pk_bf16_f32 v179, v239, v225
	v_cvt_pk_bf16_f32 v181, v224, v226
	global_store_dwordx4 v[182:183], v[178:181], off offset:256
	s_nop 1
	v_add_f32_e32 v179, 1.0, v139
	v_add_f32_e32 v178, 1.0, v140
	v_rcp_f32_e32 v180, v179
	v_add_f32_e32 v179, 1.0, v138
	v_add_f32_e32 v183, 1.0, v155
	v_add_f32_e32 v225, 1.0, v153
	v_rcp_f32_e32 v178, v178
	v_rcp_f32_e32 v179, v179
	v_add_f32_e32 v181, 1.0, v213
	v_rcp_f32_e32 v183, v183
	v_add_f32_e32 v224, 1.0, v154
	v_rcp_f32_e32 v225, v225
	v_add_f32_e32 v226, 1.0, v152
	v_rcp_f32_e32 v181, v181
	v_rcp_f32_e32 v224, v224
	v_rcp_f32_e32 v226, v226
	v_add_u32_e32 v182, 16, v0
	v_cvt_pk_bf16_f32 v178, v178, v179
	v_cvt_pk_bf16_f32 v179, v183, v225
	v_mad_i64_i32 v[182:183], s[0:1], v182, s47, v[134:135]
	v_cvt_pk_bf16_f32 v180, v180, v181
	v_cvt_pk_bf16_f32 v181, v224, v226
	v_lshl_add_u64 v[182:183], v[182:183], 0, v[136:137]
	global_store_dwordx4 v[182:183], v[178:181], off
	s_nop 1
	v_add_f32_e32 v179, 1.0, v211
	v_add_f32_e32 v178, 1.0, v212
	v_rcp_f32_e32 v180, v179
	v_add_f32_e32 v179, 1.0, v252
	v_add_f32_e32 v181, 1.0, v251
	v_add_f32_e32 v224, 1.0, v250
	v_add_f32_e32 v225, 1.0, v249
	v_add_f32_e32 v226, 1.0, v248
	v_add_f32_e32 v239, 1.0, v247
	v_rcp_f32_e32 v178, v178
	v_rcp_f32_e32 v179, v179
	v_rcp_f32_e32 v181, v181
	v_rcp_f32_e32 v224, v224
	v_rcp_f32_e32 v225, v225
	v_rcp_f32_e32 v226, v226
	v_rcp_f32_e32 v239, v239
	v_cvt_pk_bf16_f32 v178, v178, v179
	v_cvt_pk_bf16_f32 v180, v180, v181
	v_cvt_pk_bf16_f32 v179, v224, v226
	v_cvt_pk_bf16_f32 v181, v225, v239
	global_store_dwordx4 v[182:183], v[178:181], off offset:256
	s_nop 1
	v_add_f32_e32 v179, 1.0, v245
	v_add_f32_e32 v178, 1.0, v246
	v_rcp_f32_e32 v180, v179
	v_add_f32_e32 v179, 1.0, v244
	v_add_f32_e32 v183, 1.0, v242
	v_add_f32_e32 v225, 1.0, v184
	v_rcp_f32_e32 v178, v178
	v_rcp_f32_e32 v179, v179
	v_add_f32_e32 v181, 1.0, v243
	v_rcp_f32_e32 v183, v183
	v_add_f32_e32 v224, 1.0, v241
	v_rcp_f32_e32 v225, v225
	v_add_f32_e32 v226, 1.0, v177
	v_rcp_f32_e32 v181, v181
	v_rcp_f32_e32 v224, v224
	v_rcp_f32_e32 v226, v226
	v_add_u32_e32 v182, 32, v0
	v_cvt_pk_bf16_f32 v178, v178, v179
	v_cvt_pk_bf16_f32 v179, v183, v225
	v_mad_i64_i32 v[182:183], s[0:1], v182, s47, v[134:135]
	v_cvt_pk_bf16_f32 v180, v180, v181
	v_cvt_pk_bf16_f32 v181, v224, v226
	v_lshl_add_u64 v[182:183], v[182:183], 0, v[136:137]
	global_store_dwordx4 v[182:183], v[178:181], off
	s_nop 1
	v_add_f32_e32 v179, 1.0, v199
	v_add_f32_e32 v178, 1.0, v198
	v_rcp_f32_e32 v180, v179
	v_add_f32_e32 v179, 1.0, v197
	v_add_f32_e32 v181, 1.0, v196
	v_add_f32_e32 v224, 1.0, v195
	v_add_f32_e32 v225, 1.0, v194
	v_add_f32_e32 v226, 1.0, v193
	v_add_f32_e32 v239, 1.0, v192
	v_rcp_f32_e32 v178, v178
	v_rcp_f32_e32 v179, v179
	v_rcp_f32_e32 v181, v181
	v_rcp_f32_e32 v224, v224
	v_rcp_f32_e32 v225, v225
	v_rcp_f32_e32 v226, v226
	v_rcp_f32_e32 v239, v239
	v_cvt_pk_bf16_f32 v178, v178, v179
	v_cvt_pk_bf16_f32 v180, v180, v181
	v_cvt_pk_bf16_f32 v179, v224, v226
	v_cvt_pk_bf16_f32 v181, v225, v239
	global_store_dwordx4 v[182:183], v[178:181], off offset:256
	s_nop 1
	v_add_f32_e32 v179, 1.0, v190
	v_add_f32_e32 v178, 1.0, v191
	v_rcp_f32_e32 v180, v179
	v_add_f32_e32 v179, 1.0, v189
	v_add_f32_e32 v183, 1.0, v187
	v_add_f32_e32 v225, 1.0, v185
	v_rcp_f32_e32 v178, v178
	v_rcp_f32_e32 v179, v179
	v_add_f32_e32 v181, 1.0, v188
	v_rcp_f32_e32 v183, v183
	v_add_f32_e32 v224, 1.0, v186
	v_rcp_f32_e32 v225, v225
	v_add_f32_e32 v226, 1.0, v201
	v_rcp_f32_e32 v181, v181
	v_rcp_f32_e32 v224, v224
	v_rcp_f32_e32 v226, v226
	v_add_u32_e32 v182, 48, v0
	v_cvt_pk_bf16_f32 v178, v178, v179
	v_cvt_pk_bf16_f32 v179, v183, v225
	v_mad_i64_i32 v[182:183], s[0:1], v182, s47, v[134:135]
	v_cvt_pk_bf16_f32 v180, v180, v181
	v_cvt_pk_bf16_f32 v181, v224, v226
	v_lshl_add_u64 v[182:183], v[182:183], 0, v[136:137]
	global_store_dwordx4 v[182:183], v[178:181], off
	s_nop 1
	v_add_f32_e32 v179, 1.0, v221
	v_add_f32_e32 v178, 1.0, v200
	v_rcp_f32_e32 v180, v179
	v_add_f32_e32 v179, 1.0, v220
	v_add_f32_e32 v181, 1.0, v219
	v_add_f32_e32 v224, 1.0, v218
	v_add_f32_e32 v225, 1.0, v217
	v_add_f32_e32 v226, 1.0, v216
	v_add_f32_e32 v239, 1.0, v215
	v_rcp_f32_e32 v178, v178
	v_rcp_f32_e32 v179, v179
	v_rcp_f32_e32 v181, v181
	v_rcp_f32_e32 v224, v224
	v_rcp_f32_e32 v225, v225
	v_rcp_f32_e32 v226, v226
	v_rcp_f32_e32 v239, v239
	v_cvt_pk_bf16_f32 v178, v178, v179
	v_cvt_pk_bf16_f32 v180, v180, v181
	v_cvt_pk_bf16_f32 v179, v224, v226
	v_cvt_pk_bf16_f32 v181, v225, v239
	global_store_dwordx4 v[182:183], v[178:181], off offset:256
	s_nop 1
	v_add_f32_e32 v179, 1.0, v208
	v_add_f32_e32 v178, 1.0, v209
	v_rcp_f32_e32 v180, v179
	v_add_f32_e32 v179, 1.0, v207
	v_add_f32_e32 v183, 1.0, v205
	v_add_f32_e32 v225, 1.0, v203
	v_rcp_f32_e32 v178, v178
	v_rcp_f32_e32 v179, v179
	v_add_f32_e32 v181, 1.0, v206
	v_rcp_f32_e32 v183, v183
	v_add_f32_e32 v224, 1.0, v204
	v_rcp_f32_e32 v225, v225
	v_add_f32_e32 v226, 1.0, v202
	v_rcp_f32_e32 v181, v181
	v_rcp_f32_e32 v224, v224
	v_rcp_f32_e32 v226, v226
	v_add_u32_e32 v182, 0x80, v0
	v_cvt_pk_bf16_f32 v178, v178, v179
	v_cvt_pk_bf16_f32 v179, v183, v225
	v_mad_i64_i32 v[182:183], s[0:1], v182, s47, v[134:135]
	v_cvt_pk_bf16_f32 v180, v180, v181
	v_cvt_pk_bf16_f32 v181, v224, v226
	v_lshl_add_u64 v[182:183], v[182:183], 0, v[136:137]
	global_store_dwordx4 v[182:183], v[178:181], off
	s_nop 1
	v_add_f32_e32 v179, 1.0, v222
	v_rcp_f32_e32 v180, v179
	v_exp_f32_e32 v179, v237
	v_exp_f32_e32 v224, v236
	v_exp_f32_e32 v226, v234
	v_exp_f32_e32 v239, v233
	v_add_f32_e32 v179, 1.0, v179
	v_rcp_f32_e32 v225, v179
	v_exp_f32_e32 v179, v235
	v_add_f32_e32 v178, 1.0, v223
	v_add_f32_e32 v181, 1.0, v238
	v_add_f32_e32 v224, 1.0, v224
	v_add_f32_e32 v179, 1.0, v179
	v_rcp_f32_e32 v227, v179
	v_add_f32_e32 v179, 1.0, v226
	v_add_f32_e32 v226, 1.0, v239
	v_rcp_f32_e32 v178, v178
	v_rcp_f32_e32 v181, v181
	v_rcp_f32_e32 v224, v224
	v_rcp_f32_e32 v179, v179
	v_rcp_f32_e32 v226, v226
	v_cvt_pk_bf16_f32 v178, v178, v181
	v_cvt_pk_bf16_f32 v180, v180, v225
	v_cvt_pk_bf16_f32 v179, v224, v179
	v_cvt_pk_bf16_f32 v181, v227, v226
	global_store_dwordx4 v[182:183], v[178:181], off offset:256
	s_nop 1
	v_exp_f32_e32 v179, v231
	v_mul_f32_e32 v183, 0xbfb8aa3b, v52
	v_mul_f32_e32 v225, 0xbfb8aa3b, v53
	v_exp_f32_e32 v183, v183
	v_add_f32_e32 v179, 1.0, v179
	v_rcp_f32_e32 v181, v179
	v_exp_f32_e32 v179, v229
	v_exp_f32_e32 v225, v225
	v_mul_f32_e32 v226, 0xbfb8aa3b, v45
	v_exp_f32_e32 v178, v232
	v_add_f32_e32 v179, 1.0, v179
	v_rcp_f32_e32 v224, v179
	v_mul_f32_e32 v179, 0xbfb8aa3b, v44
	v_exp_f32_e32 v179, v179
	v_exp_f32_e32 v180, v230
	v_exp_f32_e32 v226, v226
	v_add_f32_e32 v183, 1.0, v183
	v_add_f32_e32 v179, 1.0, v179
	v_rcp_f32_e32 v227, v179
	v_add_f32_e32 v179, 1.0, v225
	v_add_f32_e32 v178, 1.0, v178
	v_add_f32_e32 v180, 1.0, v180
	v_rcp_f32_e32 v183, v183
	v_rcp_f32_e32 v179, v179
	v_add_f32_e32 v225, 1.0, v226
	v_rcp_f32_e32 v178, v178
	v_rcp_f32_e32 v180, v180
	v_rcp_f32_e32 v225, v225
	v_add_u32_e32 v182, 0x90, v0
	v_cvt_pk_bf16_f32 v179, v183, v179
	v_mad_i64_i32 v[182:183], s[0:1], v182, s47, v[134:135]
	v_cvt_pk_bf16_f32 v178, v178, v180
	v_cvt_pk_bf16_f32 v180, v181, v224
	v_cvt_pk_bf16_f32 v181, v227, v225
	v_lshl_add_u64 v[182:183], v[182:183], 0, v[136:137]
	global_store_dwordx4 v[182:183], v[178:181], off
	s_nop 1
	v_mul_f32_e32 v179, 0xbfb8aa3b, v30
	v_exp_f32_e32 v179, v179
	v_mul_f32_e32 v178, 0xbfb8aa3b, v38
	v_mul_f32_e32 v180, 0xbfb8aa3b, v39
	v_mul_f32_e32 v224, 0xbfb8aa3b, v40
	v_add_f32_e32 v179, 1.0, v179
	v_rcp_f32_e32 v181, v179
	v_mul_f32_e32 v179, 0xbfb8aa3b, v31
	v_exp_f32_e32 v179, v179
	v_mul_f32_e32 v226, 0xbfb8aa3b, v41
	v_mul_f32_e32 v227, 0xbfb8aa3b, v33
	v_exp_f32_e32 v178, v178
	v_add_f32_e32 v179, 1.0, v179
	v_rcp_f32_e32 v225, v179
	v_mul_f32_e32 v179, 0xbfb8aa3b, v32
	v_exp_f32_e32 v179, v179
	v_exp_f32_e32 v180, v180
	v_exp_f32_e32 v224, v224
	v_exp_f32_e32 v226, v226
	v_exp_f32_e32 v227, v227
	v_add_f32_e32 v179, 1.0, v179
	v_add_f32_e32 v178, 1.0, v178
	v_add_f32_e32 v180, 1.0, v180
	v_add_f32_e32 v224, 1.0, v224
	v_rcp_f32_e32 v239, v179
	v_add_f32_e32 v179, 1.0, v226
	v_add_f32_e32 v226, 1.0, v227
	v_rcp_f32_e32 v178, v178
	v_rcp_f32_e32 v180, v180
	v_rcp_f32_e32 v224, v224
	v_rcp_f32_e32 v179, v179
	v_rcp_f32_e32 v226, v226
	v_cvt_pk_bf16_f32 v178, v178, v180
	v_cvt_pk_bf16_f32 v180, v181, v225
	v_cvt_pk_bf16_f32 v179, v224, v179
	v_cvt_pk_bf16_f32 v181, v239, v226
	global_store_dwordx4 v[182:183], v[178:181], off offset:256
	s_nop 1
	v_mul_f32_e32 v179, 0xbfb8aa3b, v26
	v_exp_f32_e32 v179, v179
	v_mul_f32_e32 v183, 0xbfb8aa3b, v36
	v_mul_f32_e32 v225, 0xbfb8aa3b, v37
	v_mul_f32_e32 v178, 0xbfb8aa3b, v34
	v_add_f32_e32 v179, 1.0, v179
	v_rcp_f32_e32 v181, v179
	v_mul_f32_e32 v179, 0xbfb8aa3b, v27
	v_exp_f32_e32 v179, v179
	v_mul_f32_e32 v180, 0xbfb8aa3b, v35
	v_exp_f32_e32 v183, v183
	v_exp_f32_e32 v225, v225
	v_add_f32_e32 v179, 1.0, v179
	v_rcp_f32_e32 v224, v179
	v_mul_f32_e32 v179, 0xbfb8aa3b, v28
	v_exp_f32_e32 v179, v179
	v_mul_f32_e32 v226, 0xbfb8aa3b, v29
	v_exp_f32_e32 v178, v178
	v_exp_f32_e32 v180, v180
	v_exp_f32_e32 v226, v226
	v_add_f32_e32 v179, 1.0, v179
	v_add_f32_e32 v183, 1.0, v183
	v_rcp_f32_e32 v227, v179
	v_add_f32_e32 v179, 1.0, v225
	v_add_f32_e32 v178, 1.0, v178
	v_add_f32_e32 v180, 1.0, v180
	v_rcp_f32_e32 v183, v183
	v_rcp_f32_e32 v179, v179
	v_add_f32_e32 v225, 1.0, v226
	v_rcp_f32_e32 v178, v178
	v_rcp_f32_e32 v180, v180
	v_rcp_f32_e32 v225, v225
	v_add_u32_e32 v182, 0xa0, v0
	v_cvt_pk_bf16_f32 v179, v183, v179
	v_mad_i64_i32 v[182:183], s[0:1], v182, s47, v[134:135]
	v_cvt_pk_bf16_f32 v178, v178, v180
	v_cvt_pk_bf16_f32 v180, v181, v224
	v_cvt_pk_bf16_f32 v181, v227, v225
	v_lshl_add_u64 v[182:183], v[182:183], 0, v[136:137]
	global_store_dwordx4 v[182:183], v[178:181], off
	s_nop 1
	v_mul_f32_e32 v179, 0xbfb8aa3b, v14
	v_exp_f32_e32 v179, v179
	v_mul_f32_e32 v178, 0xbfb8aa3b, v22
	v_mul_f32_e32 v180, 0xbfb8aa3b, v23
	v_mul_f32_e32 v224, 0xbfb8aa3b, v24
	v_add_f32_e32 v179, 1.0, v179
	v_rcp_f32_e32 v181, v179
	v_mul_f32_e32 v179, 0xbfb8aa3b, v15
	v_exp_f32_e32 v179, v179
	v_mul_f32_e32 v226, 0xbfb8aa3b, v25
	v_mul_f32_e32 v227, 0xbfb8aa3b, v17
	v_exp_f32_e32 v178, v178
	v_add_f32_e32 v179, 1.0, v179
	v_rcp_f32_e32 v225, v179
	v_mul_f32_e32 v179, 0xbfb8aa3b, v16
	v_exp_f32_e32 v179, v179
	v_exp_f32_e32 v180, v180
	v_exp_f32_e32 v224, v224
	v_exp_f32_e32 v226, v226
	v_exp_f32_e32 v227, v227
	v_add_f32_e32 v179, 1.0, v179
	v_add_f32_e32 v178, 1.0, v178
	v_add_f32_e32 v180, 1.0, v180
	v_add_f32_e32 v224, 1.0, v224
	v_rcp_f32_e32 v239, v179
	v_add_f32_e32 v179, 1.0, v226
	v_add_f32_e32 v226, 1.0, v227
	v_rcp_f32_e32 v178, v178
	v_rcp_f32_e32 v180, v180
	v_rcp_f32_e32 v224, v224
	v_rcp_f32_e32 v179, v179
	v_rcp_f32_e32 v226, v226
	v_cvt_pk_bf16_f32 v178, v178, v180
	v_cvt_pk_bf16_f32 v180, v181, v225
	v_cvt_pk_bf16_f32 v179, v224, v179
	v_cvt_pk_bf16_f32 v181, v239, v226
	global_store_dwordx4 v[182:183], v[178:181], off offset:256
	s_nop 1
	v_mul_f32_e32 v179, 0xbfb8aa3b, v10
	v_exp_f32_e32 v179, v179
	v_mul_f32_e32 v180, 0xbfb8aa3b, v19
	v_mul_f32_e32 v181, 0xbfb8aa3b, v11
	v_exp_f32_e32 v180, v180
	v_exp_f32_e32 v181, v181
	v_add_f32_e32 v179, 1.0, v179
	v_rcp_f32_e32 v182, v179
	v_add_f32_e32 v179, 1.0, v180
	v_add_f32_e32 v180, 1.0, v181
	v_mul_f32_e32 v181, 0xbfb8aa3b, v20
	v_mul_f32_e32 v183, 0xbfb8aa3b, v12
	v_mul_f32_e32 v224, 0xbfb8aa3b, v21
	v_mul_f32_e32 v225, 0xbfb8aa3b, v13
	v_exp_f32_e32 v178, v228
	v_exp_f32_e32 v181, v181
	v_exp_f32_e32 v183, v183
	v_exp_f32_e32 v224, v224
	v_exp_f32_e32 v225, v225
	v_add_f32_e32 v178, 1.0, v178
	v_add_f32_e32 v181, 1.0, v181
	v_add_f32_e32 v183, 1.0, v183
	v_add_f32_e32 v224, 1.0, v224
	v_add_f32_e32 v225, 1.0, v225
	v_rcp_f32_e32 v178, v178
	v_rcp_f32_e32 v179, v179
	v_rcp_f32_e32 v180, v180
	v_rcp_f32_e32 v181, v181
	v_rcp_f32_e32 v183, v183
	v_rcp_f32_e32 v224, v224
	v_rcp_f32_e32 v225, v225
	v_add_u32_e32 v0, 0xb0, v0
	v_mad_i64_i32 v[134:135], s[0:1], v0, s47, v[134:135]
	v_cvt_pk_bf16_f32 v178, v178, v179
	v_cvt_pk_bf16_f32 v179, v181, v224
	v_cvt_pk_bf16_f32 v180, v182, v180
	v_cvt_pk_bf16_f32 v181, v183, v225
	v_lshl_add_u64 v[182:183], v[134:135], 0, v[136:137]
	global_store_dwordx4 v[182:183], v[178:181], off
	v_mul_f32_e32 v134, 0xbfb8aa3b, v2
	v_exp_f32_e32 v134, v134
	v_mul_f32_e32 v135, 0xbfb8aa3b, v7
	v_mul_f32_e32 v136, 0xbfb8aa3b, v3
	v_exp_f32_e32 v135, v135
	v_exp_f32_e32 v136, v136
	v_add_f32_e32 v134, 1.0, v134
	v_rcp_f32_e32 v137, v134
	v_add_f32_e32 v134, 1.0, v135
	v_add_f32_e32 v135, 1.0, v136
	v_mul_f32_e32 v136, 0xbfb8aa3b, v8
	v_mul_f32_e32 v178, 0xbfb8aa3b, v4
	v_exp_f32_e32 v136, v136
	v_exp_f32_e32 v178, v178
	v_mul_f32_e32 v0, 0xbfb8aa3b, v6
	v_rcp_f32_e32 v179, v135
	v_add_f32_e32 v135, 1.0, v136
	v_add_f32_e32 v136, 1.0, v178
	v_mul_f32_e32 v178, 0xbfb8aa3b, v9
	v_mul_f32_e32 v180, 0xbfb8aa3b, v5
	v_exp_f32_e32 v0, v0
	v_exp_f32_e32 v178, v178
	v_exp_f32_e32 v180, v180
	v_rcp_f32_e32 v181, v136
	v_add_f32_e32 v0, 1.0, v0
	v_add_f32_e32 v136, 1.0, v178
	v_add_f32_e32 v178, 1.0, v180
	v_rcp_f32_e32 v0, v0
	v_rcp_f32_e32 v134, v134
	v_rcp_f32_e32 v135, v135
	v_rcp_f32_e32 v136, v136
	v_rcp_f32_e32 v178, v178
	v_cvt_pk_bf16_f32 v134, v0, v134
	v_cvt_pk_bf16_f32 v135, v135, v136
	v_cvt_pk_bf16_f32 v136, v137, v179
	v_cvt_pk_bf16_f32 v137, v181, v178
	global_store_dwordx4 v[182:183], v[134:137], off offset:256
	s_mov_b64 s[0:1], 0

.LBB0_939:
	s_add_u32 s36, s30, 0xfff80080
	s_addc_u32 s37, s31, -1
	s_add_i32 s69, 0, 0x10000
	v_add_u32_e32 v146, s69, v140
	ds_read_b128 v[142:145], v146
	ds_read_b128 v[152:155], v146 offset:1024
	ds_read_b128 v[156:159], v146 offset:2048
	ds_read_b128 v[160:163], v146 offset:3072
	s_cmp_eq_u32 s68, 28
	s_cselect_b32 s39, s27, s37
	s_cselect_b32 s38, s26, s36
	s_cselect_b32 s37, s23, s67
	s_cselect_b32 s36, s42, s43
	s_add_i32 m0, s41, 0xc000
	ds_read_b128 v[164:167], v141
	ds_read_b128 v[168:171], v141 offset:1024
	ds_read_b128 v[172:175], v141 offset:2048
	ds_read_b128 v[176:179], v141 offset:3072
	ds_read_b128 v[180:183], v141 offset:4096
	ds_read_b128 v[184:187], v141 offset:5120
	ds_read_b128 v[188:191], v141 offset:6144
	ds_read_b128 v[192:195], v141 offset:7168
	global_load_lds_dwordx4 v136, s[30:31]
	s_add_i32 m0, s41, 0xe000
	s_nop 0
	global_load_lds_dwordx4 v138, s[30:31]
	s_waitcnt lgkmcnt(8)
	s_barrier
	s_setprio 1
	s_waitcnt lgkmcnt(7)
	v_mfma_f32_16x16x32_bf16 v[126:129], v[142:145], v[164:167], v[126:129]
	v_mfma_f32_16x16x32_bf16 v[122:125], v[156:159], v[164:167], v[122:125]
	s_waitcnt lgkmcnt(5)
	v_mfma_f32_16x16x32_bf16 v[118:121], v[142:145], v[172:175], v[118:121]
	v_mfma_f32_16x16x32_bf16 v[114:117], v[156:159], v[172:175], v[114:117]
	s_waitcnt lgkmcnt(3)
	v_mfma_f32_16x16x32_bf16 v[102:105], v[142:145], v[180:183], v[102:105]
	v_mfma_f32_16x16x32_bf16 v[98:101], v[156:159], v[180:183], v[98:101]
	s_waitcnt lgkmcnt(1)
	v_mfma_f32_16x16x32_bf16 v[86:89], v[142:145], v[188:191], v[86:89]
	v_mfma_f32_16x16x32_bf16 v[82:85], v[156:159], v[188:191], v[82:85]
	v_mfma_f32_16x16x32_bf16 v[126:129], v[152:155], v[168:171], v[126:129]
	v_mfma_f32_16x16x32_bf16 v[122:125], v[160:163], v[168:171], v[122:125]
	v_mfma_f32_16x16x32_bf16 v[118:121], v[152:155], v[176:179], v[118:121]
	v_mfma_f32_16x16x32_bf16 v[114:117], v[160:163], v[176:179], v[114:117]
	v_mfma_f32_16x16x32_bf16 v[102:105], v[152:155], v[184:187], v[102:105]
	v_mfma_f32_16x16x32_bf16 v[98:101], v[160:163], v[184:187], v[98:101]
	s_waitcnt lgkmcnt(0)
	v_mfma_f32_16x16x32_bf16 v[86:89], v[152:155], v[192:195], v[86:89]
	v_mfma_f32_16x16x32_bf16 v[82:85], v[160:163], v[192:195], v[82:85]
	s_setprio 0
	s_barrier
	s_add_i32 s75, 0, 0x14000
	v_add_u32_e32 v146, s75, v140
	s_add_i32 s69, s69, s40
	ds_read_b128 v[196:199], v146
	ds_read_b128 v[200:203], v146 offset:1024
	ds_read_b128 v[204:207], v146 offset:2048
	ds_read_b128 v[216:219], v146 offset:3072
	s_mov_b32 m0, s69
	s_nop 0
	global_load_lds_dwordx4 v0, s[36:37]
	s_add_i32 m0, s69, 0x2000
	s_nop 0
	global_load_lds_dwordx4 v130, s[36:37]
	s_barrier
	s_setprio 1
	s_waitcnt lgkmcnt(3)
	v_mfma_f32_16x16x32_bf16 v[110:113], v[196:199], v[164:167], v[110:113]
	s_waitcnt lgkmcnt(1)
	v_mfma_f32_16x16x32_bf16 v[106:109], v[204:207], v[164:167], v[106:109]
	v_mfma_f32_16x16x32_bf16 v[94:97], v[196:199], v[172:175], v[94:97]
	v_mfma_f32_16x16x32_bf16 v[90:93], v[204:207], v[172:175], v[90:93]
	v_mfma_f32_16x16x32_bf16 v[78:81], v[196:199], v[180:183], v[78:81]
	v_mfma_f32_16x16x32_bf16 v[74:77], v[204:207], v[180:183], v[74:77]
	v_mfma_f32_16x16x32_bf16 v[70:73], v[196:199], v[188:191], v[70:73]
	v_mfma_f32_16x16x32_bf16 v[66:69], v[204:207], v[188:191], v[66:69]
	v_mfma_f32_16x16x32_bf16 v[110:113], v[200:203], v[168:171], v[110:113]
	s_waitcnt lgkmcnt(0)
	v_mfma_f32_16x16x32_bf16 v[106:109], v[216:219], v[168:171], v[106:109]
	v_mfma_f32_16x16x32_bf16 v[94:97], v[200:203], v[176:179], v[94:97]
	v_mfma_f32_16x16x32_bf16 v[90:93], v[216:219], v[176:179], v[90:93]
	v_mfma_f32_16x16x32_bf16 v[78:81], v[200:203], v[184:187], v[78:81]
	v_mfma_f32_16x16x32_bf16 v[74:77], v[216:219], v[184:187], v[74:77]
	v_mfma_f32_16x16x32_bf16 v[70:73], v[200:203], v[192:195], v[70:73]
	v_mfma_f32_16x16x32_bf16 v[66:69], v[216:219], v[192:195], v[66:69]
	s_setprio 0
	s_mov_b32 m0, s41
	s_add_u32 s98, s38, 0x80
	s_addc_u32 s99, s39, 0
	s_barrier
	ds_read_b128 v[164:167], v141 offset:16384
	ds_read_b128 v[168:171], v141 offset:17408
	ds_read_b128 v[172:175], v141 offset:18432
	ds_read_b128 v[176:179], v141 offset:19456
	ds_read_b128 v[180:183], v141 offset:20480
	ds_read_b128 v[184:187], v141 offset:21504
	ds_read_b128 v[188:191], v141 offset:22528
	ds_read_b128 v[192:195], v141 offset:23552
	global_load_lds_dwordx4 v134, s[38:39]
	s_mov_b32 m0, s44
	s_nop 0
	global_load_lds_dwordx4 v132, s[38:39]
	s_barrier
	s_setprio 1
	s_waitcnt lgkmcnt(7)
	v_mfma_f32_16x16x32_bf16 v[62:65], v[142:145], v[164:167], v[62:65]
	v_mfma_f32_16x16x32_bf16 v[58:61], v[156:159], v[164:167], v[58:61]
	s_waitcnt lgkmcnt(5)
	v_mfma_f32_16x16x32_bf16 v[54:57], v[142:145], v[172:175], v[54:57]
	v_mfma_f32_16x16x32_bf16 v[50:53], v[156:159], v[172:175], v[50:53]
	s_waitcnt lgkmcnt(3)
	v_mfma_f32_16x16x32_bf16 v[38:41], v[142:145], v[180:183], v[38:41]
	v_mfma_f32_16x16x32_bf16 v[34:37], v[156:159], v[180:183], v[34:37]
	s_waitcnt lgkmcnt(1)
	v_mfma_f32_16x16x32_bf16 v[22:25], v[142:145], v[188:191], v[22:25]
	v_mfma_f32_16x16x32_bf16 v[18:21], v[156:159], v[188:191], v[18:21]
	v_mfma_f32_16x16x32_bf16 v[62:65], v[152:155], v[168:171], v[62:65]
	v_mfma_f32_16x16x32_bf16 v[58:61], v[160:163], v[168:171], v[58:61]
	v_mfma_f32_16x16x32_bf16 v[54:57], v[152:155], v[176:179], v[54:57]
	v_mfma_f32_16x16x32_bf16 v[50:53], v[160:163], v[176:179], v[50:53]
	v_mfma_f32_16x16x32_bf16 v[38:41], v[152:155], v[184:187], v[38:41]
	v_mfma_f32_16x16x32_bf16 v[34:37], v[160:163], v[184:187], v[34:37]
	s_waitcnt lgkmcnt(0)
	v_mfma_f32_16x16x32_bf16 v[22:25], v[152:155], v[192:195], v[22:25]
	v_mfma_f32_16x16x32_bf16 v[18:21], v[160:163], v[192:195], v[18:21]
	s_setprio 0
	s_barrier
	s_add_u32 s76, s36, 0x80000
	s_addc_u32 s77, s37, 0
	s_add_i32 s69, s75, s40
	s_mov_b32 m0, s69
	s_nop 0
	global_load_lds_dwordx4 v0, s[76:77]
	s_add_i32 m0, s69, 0x2000
	s_nop 0
	global_load_lds_dwordx4 v130, s[76:77]
	s_waitcnt vmcnt(6)
	s_barrier
	s_setprio 1
	v_mfma_f32_16x16x32_bf16 v[46:49], v[196:199], v[164:167], v[46:49]
	v_mfma_f32_16x16x32_bf16 v[42:45], v[204:207], v[164:167], v[42:45]
	v_mfma_f32_16x16x32_bf16 v[30:33], v[196:199], v[172:175], v[30:33]
	v_mfma_f32_16x16x32_bf16 v[26:29], v[204:207], v[172:175], v[26:29]
	v_mfma_f32_16x16x32_bf16 v[14:17], v[196:199], v[180:183], v[14:17]
	v_mfma_f32_16x16x32_bf16 v[10:13], v[204:207], v[180:183], v[10:13]
	v_mfma_f32_16x16x32_bf16 v[6:9], v[196:199], v[188:191], v[6:9]
	v_mfma_f32_16x16x32_bf16 v[2:5], v[204:207], v[188:191], v[2:5]
	v_mfma_f32_16x16x32_bf16 v[46:49], v[200:203], v[168:171], v[46:49]
	v_mfma_f32_16x16x32_bf16 v[42:45], v[216:219], v[168:171], v[42:45]
	v_mfma_f32_16x16x32_bf16 v[30:33], v[200:203], v[176:179], v[30:33]
	v_mfma_f32_16x16x32_bf16 v[26:29], v[216:219], v[176:179], v[26:29]
	v_mfma_f32_16x16x32_bf16 v[14:17], v[200:203], v[184:187], v[14:17]
	v_mfma_f32_16x16x32_bf16 v[10:13], v[216:219], v[184:187], v[10:13]
	v_mfma_f32_16x16x32_bf16 v[6:9], v[200:203], v[192:195], v[6:9]
	v_mfma_f32_16x16x32_bf16 v[2:5], v[216:219], v[192:195], v[2:5]
	s_setprio 0
	s_add_i32 s69, 0, 0x18000
	v_add_u32_e32 v149, s69, v140
	s_barrier
	ds_read_b128 v[142:145], v149
	ds_read_b128 v[152:155], v149 offset:1024
	ds_read_b128 v[156:159], v149 offset:2048
	ds_read_b128 v[160:163], v149 offset:3072
	s_add_u32 s38, s38, 0x80000
	s_addc_u32 s39, s39, 0
	s_mov_b32 m0, s45
	ds_read_b128 v[164:167], v141 offset:32768
	ds_read_b128 v[168:171], v141 offset:33792
	ds_read_b128 v[172:175], v141 offset:34816
	ds_read_b128 v[176:179], v141 offset:35840
	ds_read_b128 v[180:183], v141 offset:36864
	ds_read_b128 v[184:187], v141 offset:37888
	ds_read_b128 v[188:191], v141 offset:38912
	ds_read_b128 v[192:195], v141 offset:39936
	global_load_lds_dwordx4 v134, s[38:39]
	s_mov_b32 m0, s50
	s_nop 0
	global_load_lds_dwordx4 v132, s[38:39]
	s_waitcnt lgkmcnt(8)
	s_barrier
	s_setprio 1
	s_waitcnt lgkmcnt(7)
	v_mfma_f32_16x16x32_bf16 v[126:129], v[142:145], v[164:167], v[126:129]
	v_mfma_f32_16x16x32_bf16 v[122:125], v[156:159], v[164:167], v[122:125]
	s_waitcnt lgkmcnt(5)
	v_mfma_f32_16x16x32_bf16 v[118:121], v[142:145], v[172:175], v[118:121]
	v_mfma_f32_16x16x32_bf16 v[114:117], v[156:159], v[172:175], v[114:117]
	s_waitcnt lgkmcnt(3)
	v_mfma_f32_16x16x32_bf16 v[102:105], v[142:145], v[180:183], v[102:105]
	v_mfma_f32_16x16x32_bf16 v[98:101], v[156:159], v[180:183], v[98:101]
	s_waitcnt lgkmcnt(1)
	v_mfma_f32_16x16x32_bf16 v[86:89], v[142:145], v[188:191], v[86:89]
	v_mfma_f32_16x16x32_bf16 v[82:85], v[156:159], v[188:191], v[82:85]
	v_mfma_f32_16x16x32_bf16 v[126:129], v[152:155], v[168:171], v[126:129]
	v_mfma_f32_16x16x32_bf16 v[122:125], v[160:163], v[168:171], v[122:125]
	v_mfma_f32_16x16x32_bf16 v[118:121], v[152:155], v[176:179], v[118:121]
	v_mfma_f32_16x16x32_bf16 v[114:117], v[160:163], v[176:179], v[114:117]
	v_mfma_f32_16x16x32_bf16 v[102:105], v[152:155], v[184:187], v[102:105]
	v_mfma_f32_16x16x32_bf16 v[98:101], v[160:163], v[184:187], v[98:101]
	s_waitcnt lgkmcnt(0)
	v_mfma_f32_16x16x32_bf16 v[86:89], v[152:155], v[192:195], v[86:89]
	v_mfma_f32_16x16x32_bf16 v[82:85], v[160:163], v[192:195], v[82:85]
	s_setprio 0
	s_barrier
	s_add_i32 s38, 0, 0x1c000
	s_add_i32 s39, s69, s40
	v_add_u32_e32 v149, s38, v140
	s_add_u32 s100, s36, 0x80
	s_addc_u32 s101, s37, 0
	s_mov_b32 m0, s39
	ds_read_b128 v[196:199], v149
	ds_read_b128 v[200:203], v149 offset:1024
	ds_read_b128 v[204:207], v149 offset:2048
	ds_read_b128 v[216:219], v149 offset:3072
	global_load_lds_dwordx4 v0, s[100:101]
	s_add_i32 m0, s39, 0x2000
	s_nop 0
	global_load_lds_dwordx4 v130, s[100:101]
	s_barrier
	s_setprio 1
	s_waitcnt lgkmcnt(3)
	v_mfma_f32_16x16x32_bf16 v[110:113], v[196:199], v[164:167], v[110:113]
	s_waitcnt lgkmcnt(1)
	v_mfma_f32_16x16x32_bf16 v[106:109], v[204:207], v[164:167], v[106:109]
	v_mfma_f32_16x16x32_bf16 v[94:97], v[196:199], v[172:175], v[94:97]
	v_mfma_f32_16x16x32_bf16 v[90:93], v[204:207], v[172:175], v[90:93]
	v_mfma_f32_16x16x32_bf16 v[78:81], v[196:199], v[180:183], v[78:81]
	v_mfma_f32_16x16x32_bf16 v[74:77], v[204:207], v[180:183], v[74:77]
	v_mfma_f32_16x16x32_bf16 v[70:73], v[196:199], v[188:191], v[70:73]
	v_mfma_f32_16x16x32_bf16 v[66:69], v[204:207], v[188:191], v[66:69]
	v_mfma_f32_16x16x32_bf16 v[110:113], v[200:203], v[168:171], v[110:113]
	s_waitcnt lgkmcnt(0)
	v_mfma_f32_16x16x32_bf16 v[106:109], v[216:219], v[168:171], v[106:109]
	v_mfma_f32_16x16x32_bf16 v[94:97], v[200:203], v[176:179], v[94:97]
	v_mfma_f32_16x16x32_bf16 v[90:93], v[216:219], v[176:179], v[90:93]
	v_mfma_f32_16x16x32_bf16 v[78:81], v[200:203], v[184:187], v[78:81]
	v_mfma_f32_16x16x32_bf16 v[74:77], v[216:219], v[184:187], v[74:77]
	v_mfma_f32_16x16x32_bf16 v[70:73], v[200:203], v[192:195], v[70:73]
	v_mfma_f32_16x16x32_bf16 v[66:69], v[216:219], v[192:195], v[66:69]
	s_setprio 0
	s_mov_b32 m0, s52
	s_barrier
	ds_read_b128 v[164:167], v141 offset:49152
	ds_read_b128 v[168:171], v141 offset:50176
	ds_read_b128 v[172:175], v141 offset:51200
	ds_read_b128 v[176:179], v141 offset:52224
	ds_read_b128 v[180:183], v141 offset:53248
	ds_read_b128 v[184:187], v141 offset:54272
	ds_read_b128 v[188:191], v141 offset:55296
	ds_read_b128 v[192:195], v141 offset:56320
	global_load_lds_dwordx4 v134, s[98:99]
	s_mov_b32 m0, s53
	s_nop 0
	global_load_lds_dwordx4 v132, s[98:99]
	s_barrier
	s_setprio 1
	s_waitcnt lgkmcnt(7)
	v_mfma_f32_16x16x32_bf16 v[62:65], v[142:145], v[164:167], v[62:65]
	v_mfma_f32_16x16x32_bf16 v[58:61], v[156:159], v[164:167], v[58:61]
	s_waitcnt lgkmcnt(5)
	v_mfma_f32_16x16x32_bf16 v[54:57], v[142:145], v[172:175], v[54:57]
	v_mfma_f32_16x16x32_bf16 v[50:53], v[156:159], v[172:175], v[50:53]
	s_waitcnt lgkmcnt(3)
	v_mfma_f32_16x16x32_bf16 v[38:41], v[142:145], v[180:183], v[38:41]
	v_mfma_f32_16x16x32_bf16 v[34:37], v[156:159], v[180:183], v[34:37]
	s_waitcnt lgkmcnt(1)
	v_mfma_f32_16x16x32_bf16 v[22:25], v[142:145], v[188:191], v[22:25]
	v_mfma_f32_16x16x32_bf16 v[18:21], v[156:159], v[188:191], v[18:21]
	v_mfma_f32_16x16x32_bf16 v[62:65], v[152:155], v[168:171], v[62:65]
	v_mfma_f32_16x16x32_bf16 v[58:61], v[160:163], v[168:171], v[58:61]
	v_mfma_f32_16x16x32_bf16 v[54:57], v[152:155], v[176:179], v[54:57]
	v_mfma_f32_16x16x32_bf16 v[50:53], v[160:163], v[176:179], v[50:53]
	v_mfma_f32_16x16x32_bf16 v[38:41], v[152:155], v[184:187], v[38:41]
	v_mfma_f32_16x16x32_bf16 v[34:37], v[160:163], v[184:187], v[34:37]
	s_waitcnt lgkmcnt(0)
	v_mfma_f32_16x16x32_bf16 v[22:25], v[152:155], v[192:195], v[22:25]
	v_mfma_f32_16x16x32_bf16 v[18:21], v[160:163], v[192:195], v[18:21]
	s_setprio 0
	s_barrier
	s_add_u32 s36, s36, 0x80080
	s_addc_u32 s37, s37, 0
	s_add_i32 s38, s38, s40
	s_mov_b32 m0, s38
	s_nop 0
	global_load_lds_dwordx4 v0, s[36:37]
	s_add_i32 m0, s38, 0x2000
	s_nop 0
	global_load_lds_dwordx4 v130, s[36:37]
	s_waitcnt vmcnt(6)
	s_barrier
	s_setprio 1
	v_mfma_f32_16x16x32_bf16 v[46:49], v[196:199], v[164:167], v[46:49]
	v_mfma_f32_16x16x32_bf16 v[42:45], v[204:207], v[164:167], v[42:45]
	v_mfma_f32_16x16x32_bf16 v[30:33], v[196:199], v[172:175], v[30:33]
	v_mfma_f32_16x16x32_bf16 v[26:29], v[204:207], v[172:175], v[26:29]
	v_mfma_f32_16x16x32_bf16 v[14:17], v[196:199], v[180:183], v[14:17]
	v_mfma_f32_16x16x32_bf16 v[10:13], v[204:207], v[180:183], v[10:13]
	v_mfma_f32_16x16x32_bf16 v[6:9], v[196:199], v[188:191], v[6:9]
	v_mfma_f32_16x16x32_bf16 v[2:5], v[204:207], v[188:191], v[2:5]
	v_mfma_f32_16x16x32_bf16 v[46:49], v[200:203], v[168:171], v[46:49]
	v_mfma_f32_16x16x32_bf16 v[42:45], v[216:219], v[168:171], v[42:45]
	v_mfma_f32_16x16x32_bf16 v[30:33], v[200:203], v[176:179], v[30:33]
	v_mfma_f32_16x16x32_bf16 v[26:29], v[216:219], v[176:179], v[26:29]
	v_mfma_f32_16x16x32_bf16 v[14:17], v[200:203], v[184:187], v[14:17]
	v_mfma_f32_16x16x32_bf16 v[10:13], v[216:219], v[184:187], v[10:13]
	v_mfma_f32_16x16x32_bf16 v[6:9], v[200:203], v[192:195], v[6:9]
	v_mfma_f32_16x16x32_bf16 v[2:5], v[216:219], v[192:195], v[2:5]
	s_setprio 0
	s_add_i32 s68, s68, 2
	s_add_u32 s30, s30, 0x100
	s_addc_u32 s31, s31, 0
	s_add_u32 s43, s43, 0x100
	s_addc_u32 s67, s67, 0
	s_cmp_gt_u32 s68, 29
	s_barrier
	s_cbranch_scc0 .LBB0_939
	s_lshr_b32 s23, s66, 3
	s_mulk_i32 s23, 0x880
	s_lshl_b32 s30, s66, 8
	v_mov_b32_e32 v142, v148
	s_and_b32 s30, s30, 0x700
	s_add_i32 s23, s60, s23
	s_add_i32 s23, s23, s30
	v_and_or_b32 v144, v142, 15, s23
	s_lshl_b32 s23, s65, 8
	v_lshrrev_b32_e32 v142, 1, v142
	v_and_or_b32 v142, v142, 24, s23
	v_or_b32_e32 v142, s51, v142
	v_cvt_pk_bf16_f32 v126, v126, v127
	v_cvt_pk_bf16_f32 v127, v128, v129
	v_cvt_pk_bf16_f32 v128, v122, v123
	v_mov_b64_e32 v[122:123], s[6:7]
	v_ashrrev_i32_e32 v143, 31, v142
	v_cvt_pk_bf16_f32 v70, v70, v71
	v_cvt_pk_bf16_f32 v71, v72, v73
	v_cvt_pk_bf16_f32 v72, v66, v67
	v_add_u32_e32 v66, 0x80, v144
	v_cvt_pk_bf16_f32 v129, v124, v125
	v_mad_i64_i32 v[124:125], s[30:31], v144, s74, v[122:123]
	v_lshlrev_b64 v[142:143], 1, v[142:143]
	v_cvt_pk_bf16_f32 v62, v62, v63
	v_cvt_pk_bf16_f32 v63, v64, v65
	v_cvt_pk_bf16_f32 v64, v58, v59
	v_mad_i64_i32 v[58:59], s[30:31], v66, s74, v[122:123]
	v_lshl_add_u64 v[124:125], v[124:125], 0, v[142:143]
	v_cvt_pk_bf16_f32 v110, v110, v111
	v_cvt_pk_bf16_f32 v111, v112, v113
	v_cvt_pk_bf16_f32 v112, v106, v107
	v_cvt_pk_bf16_f32 v113, v108, v109
	v_lshl_add_u64 v[58:59], v[58:59], 0, v[142:143]
	v_cvt_pk_bf16_f32 v46, v46, v47
	v_cvt_pk_bf16_f32 v47, v48, v49
	v_cvt_pk_bf16_f32 v48, v42, v43
	v_cvt_pk_bf16_f32 v49, v44, v45
	global_store_dwordx4 v[124:125], v[110:113], off offset:256
	global_store_dwordx4 v[58:59], v[46:49], off offset:256
	v_cvt_pk_bf16_f32 v94, v94, v95
	v_add_u32_e32 v110, 16, v144
	v_add_u32_e32 v46, 0x90, v144
	v_mad_i64_i32 v[110:111], s[30:31], v110, s74, v[122:123]
	v_mad_i64_i32 v[46:47], s[30:31], v46, s74, v[122:123]
	v_lshl_add_u64 v[110:111], v[110:111], 0, v[142:143]
	v_cvt_pk_bf16_f32 v95, v96, v97
	v_cvt_pk_bf16_f32 v96, v90, v91
	v_cvt_pk_bf16_f32 v97, v92, v93
	v_lshl_add_u64 v[46:47], v[46:47], 0, v[142:143]
	v_cvt_pk_bf16_f32 v30, v30, v31
	v_cvt_pk_bf16_f32 v31, v32, v33
	v_cvt_pk_bf16_f32 v32, v26, v27
	v_cvt_pk_bf16_f32 v33, v28, v29
	global_store_dwordx4 v[110:111], v[94:97], off offset:256
	global_store_dwordx4 v[46:47], v[30:33], off offset:256
	v_cvt_pk_bf16_f32 v78, v78, v79
	v_add_u32_e32 v94, 32, v144
	v_add_u32_e32 v30, 0xa0, v144
	v_mad_i64_i32 v[94:95], s[30:31], v94, s74, v[122:123]
	v_mad_i64_i32 v[30:31], s[30:31], v30, s74, v[122:123]
	v_lshl_add_u64 v[94:95], v[94:95], 0, v[142:143]
	v_cvt_pk_bf16_f32 v79, v80, v81
	v_cvt_pk_bf16_f32 v80, v74, v75
	v_cvt_pk_bf16_f32 v81, v76, v77
	v_lshl_add_u64 v[30:31], v[30:31], 0, v[142:143]
	v_cvt_pk_bf16_f32 v14, v14, v15
	v_cvt_pk_bf16_f32 v15, v16, v17
	v_cvt_pk_bf16_f32 v16, v10, v11
	v_cvt_pk_bf16_f32 v17, v12, v13
	global_store_dwordx4 v[94:95], v[78:81], off offset:256
	global_store_dwordx4 v[30:31], v[14:17], off offset:256
	v_cvt_pk_bf16_f32 v106, v118, v119
	v_add_u32_e32 v78, 48, v144
	v_add_u32_e32 v14, 0xb0, v144
	v_mad_i64_i32 v[78:79], s[30:31], v78, s74, v[122:123]
	v_mad_i64_i32 v[14:15], s[30:31], v14, s74, v[122:123]
	v_cvt_pk_bf16_f32 v107, v120, v121
	v_cvt_pk_bf16_f32 v108, v114, v115
	v_cvt_pk_bf16_f32 v109, v116, v117
	v_cvt_pk_bf16_f32 v90, v102, v103
	v_cvt_pk_bf16_f32 v91, v104, v105
	v_cvt_pk_bf16_f32 v92, v98, v99
	v_cvt_pk_bf16_f32 v93, v100, v101
	v_cvt_pk_bf16_f32 v74, v86, v87
	v_cvt_pk_bf16_f32 v75, v88, v89
	v_cvt_pk_bf16_f32 v76, v82, v83
	v_cvt_pk_bf16_f32 v77, v84, v85
	v_lshl_add_u64 v[78:79], v[78:79], 0, v[142:143]
	v_cvt_pk_bf16_f32 v73, v68, v69
	v_cvt_pk_bf16_f32 v65, v60, v61
	v_cvt_pk_bf16_f32 v42, v54, v55
	v_cvt_pk_bf16_f32 v43, v56, v57
	v_cvt_pk_bf16_f32 v44, v50, v51
	v_cvt_pk_bf16_f32 v45, v52, v53
	v_cvt_pk_bf16_f32 v26, v38, v39
	v_cvt_pk_bf16_f32 v27, v40, v41
	v_cvt_pk_bf16_f32 v28, v34, v35
	v_cvt_pk_bf16_f32 v29, v36, v37
	v_cvt_pk_bf16_f32 v10, v22, v23
	v_cvt_pk_bf16_f32 v11, v24, v25
	v_cvt_pk_bf16_f32 v12, v18, v19
	v_cvt_pk_bf16_f32 v13, v20, v21
	v_lshl_add_u64 v[14:15], v[14:15], 0, v[142:143]
	v_cvt_pk_bf16_f32 v6, v6, v7
	v_cvt_pk_bf16_f32 v7, v8, v9
	v_cvt_pk_bf16_f32 v8, v2, v3
	v_cvt_pk_bf16_f32 v9, v4, v5
	s_and_b64 vcc, exec, s[0:1]
	s_mov_b32 s65, s22
	s_mov_b32 s66, s64
	s_mov_b64 s[36:37], s[28:29]
	s_mov_b64 s[30:31], s[26:27]
	global_store_dwordx4 v[124:125], v[126:129], off
	global_store_dwordx4 v[110:111], v[106:109], off
	global_store_dwordx4 v[94:95], v[90:93], off
	global_store_dwordx4 v[78:79], v[74:77], off
	global_store_dwordx4 v[78:79], v[70:73], off offset:256
	global_store_dwordx4 v[58:59], v[62:65], off
	global_store_dwordx4 v[46:47], v[42:45], off
	global_store_dwordx4 v[30:31], v[26:29], off
	global_store_dwordx4 v[14:15], v[10:13], off
	global_store_dwordx4 v[14:15], v[6:9], off offset:256
	s_cbranch_vccz .LBB0_934
	s_waitcnt vmcnt(0)
	s_cmpk_gt_u32 s14, 0xff
	s_cbranch_scc1 .LBB0_943
	s_barrier
